# split LDS waits in the K-loop: reads for the first 8 MFMAs issued first, lgkmcnt(N/2) before the handoff barrier and lgkmcnt(0) before the 9th MFMA
# baseline (speedup 1.0000x reference)
; #define PG8_STAGE(bufoff, gbase, voff) do { _Pragma("unroll") for (int _i = 0; _i < 2; ++_i) \
;         __builtin_amdgcn_global_load_lds((const unsigned*)((const char*)(gbase) + (voff)[_i]), (LAS unsigned*)(lds + (bufoff) + ldsw + _i * 8192), 16, 0, 0); } while (0)
; #define PG8_LDA(dst, b, h) do { _Pragma("unroll") for (int m = 0; m < 4; ++m) _Pragma("unroll") for (int k = 0; k < 2; ++k) dst[m][k] = *(const LAS bf16x8*)(lds + PG8_SA(b, h) + aoff + m * 2048 + k * 1024); } while (0)
; #define PG8_LDB(dst, b, h) do { _Pragma("unroll") for (int n = 0; n < 2; ++n) _Pragma("unroll") for (int k = 0; k < 2; ++k) dst[n][k] = *(const LAS bf16x8*)(lds + PG8_SB(b, h) + boff + n * 2048 + k * 1024); } while (0)
; #define PG8_MMA(ai, bj, At, Bt) do { __builtin_amdgcn_s_setprio(1); _Pragma("unroll") for (int m = 0; m < 4; ++m) _Pragma("unroll") for (int n = 0; n < 2; ++n) _Pragma("unroll") for (int k = 0; k < 2; ++k) \
;         acc[ai][bj][m][n] = __builtin_amdgcn_mfma_f32_16x16x32_bf16(Bt[n][k], At[m][k], acc[ai][bj][m][n], 0, 0, 0); __builtin_amdgcn_s_setprio(0); } while (0)
; #define PG8_WAIT_V(n) asm volatile("s_waitcnt vmcnt(" #n ")" ::: "memory")
; #define PG8_WAIT_L(n) asm volatile("s_waitcnt lgkmcnt(" #n ")" ::: "memory")
; #define PG8_BAR __builtin_amdgcn_s_barrier()
; template <class Epi>
; __device__ __forceinline__ void gemm_phase(LAS unsigned char* lds, const Gemm g, const StaticOrder& S, const Epi& E) {
;     ...
;         for (; t < tend; t += 2) {
;             const bool last = (t == nt - 2);
;             const char* a1 = cA + (size_t)(t + 1) * kstep;
;             const char* a2 = last ? nA : cA + (size_t)(t + 2) * kstep; const char* b2 = last ? nB : cB + (size_t)(t + 2) * kstep;
;             const char* a3 = a2 + kstep; const char* b3 = b2 + kstep;
;             PG8_LDB(B0, 0, 0); PG8_SCHED; PG8_LDA(At, 0, 0); PG8_STAGE(PG8_SA(1, 1), a1 + hstep, voffA);
;             PG8_WAIT_L(8); PG8_BAR; PG8_WAIT_L(0); PG8_MMA(0, 0, At, B0); PG8_BAR; PG8_SCHED;
;             PG8_LDB(B1, 0, 1); PG8_STAGE(PG8_SB(0, 0), b2, voffB);
;             PG8_BAR; PG8_WAIT_L(0); PG8_MMA(0, 1, At, B1); PG8_BAR;
;             PG8_LDA(At, 0, 1); PG8_STAGE(PG8_SA(0, 0), a2, voffA);
;             PG8_BAR; PG8_WAIT_L(0); PG8_MMA(1, 0, At, B0); PG8_BAR; PG8_SCHED;
;             PG8_STAGE(PG8_SB(0, 1), b2 + hstep, voffB);
;             PG8_WAIT_V(6); PG8_BAR; PG8_MMA(1, 1, At, B1); PG8_BAR;
.LBB0_206:
	s_add_i32 s78, 0, 0x10000
	ds_read_b128 v[132:135], v234
	ds_read_b128 v[140:143], v234 offset:2048
	ds_read_b128 v[148:151], v200
	ds_read_b128 v[156:159], v200 offset:2048
	s_add_i32 s76, s2, 1
	s_mov_b32 s47, s2
	s_add_i32 s2, s2, 2
	s_ashr_i32 s77, s76, 31
	s_cmp_eq_u32 s67, s47
	s_cselect_b32 s75, s43, s46
	s_cselect_b32 s74, s42, vcc_hi
	s_cselect_b32 s93, s63, vcc_lo
	s_cselect_b32 s92, s62, s3
	s_lshl_b64 s[76:77], s[76:77], 7
	s_add_u32 s76, s5, s76
	s_addc_u32 s77, s31, s77
	s_add_i32 m0, s11, 0xc000
	ds_read_b128 v[164:167], v200 offset:4096
	ds_read_b128 v[190:193], v200 offset:6144
	ds_read_b128 v[136:139], v234 offset:1024
	ds_read_b128 v[144:147], v234 offset:3072
	ds_read_b128 v[152:155], v200 offset:1024
	ds_read_b128 v[160:163], v200 offset:3072
	ds_read_b128 v[186:189], v200 offset:5120
	ds_read_b128 v[202:205], v200 offset:7168
	global_load_lds_dwordx4 v168, s[76:77]
	s_add_i32 m0, s11, 0xe000
	s_nop 0
	global_load_lds_dwordx4 v172, s[76:77]
	s_waitcnt lgkmcnt(6)
	s_barrier
	v_mfma_f32_16x16x32_bf16 v[128:131], v[132:135], v[148:151], v[128:131]
	v_mfma_f32_16x16x32_bf16 v[124:127], v[140:143], v[148:151], v[124:127]
	v_mfma_f32_16x16x32_bf16 v[112:115], v[132:135], v[156:159], v[112:115]
	v_mfma_f32_16x16x32_bf16 v[108:111], v[140:143], v[156:159], v[108:111]
	v_mfma_f32_16x16x32_bf16 v[96:99], v[132:135], v[164:167], v[96:99]
	v_mfma_f32_16x16x32_bf16 v[92:95], v[140:143], v[164:167], v[92:95]
	v_mfma_f32_16x16x32_bf16 v[80:83], v[132:135], v[190:193], v[80:83]
	v_mfma_f32_16x16x32_bf16 v[76:79], v[140:143], v[190:193], v[76:79]
	s_waitcnt lgkmcnt(0)
	v_mfma_f32_16x16x32_bf16 v[128:131], v[136:139], v[152:155], v[128:131]
	v_mfma_f32_16x16x32_bf16 v[124:127], v[144:147], v[152:155], v[124:127]
	v_mfma_f32_16x16x32_bf16 v[112:115], v[136:139], v[160:163], v[112:115]
	v_mfma_f32_16x16x32_bf16 v[108:111], v[144:147], v[160:163], v[108:111]
	v_mfma_f32_16x16x32_bf16 v[96:99], v[136:139], v[186:189], v[96:99]
	v_mfma_f32_16x16x32_bf16 v[92:95], v[144:147], v[186:189], v[92:95]
	v_mfma_f32_16x16x32_bf16 v[80:83], v[136:139], v[202:205], v[80:83]
	v_mfma_f32_16x16x32_bf16 v[76:79], v[144:147], v[202:205], v[76:79]
	s_barrier
	s_add_i32 s47, 0, 0x14000
	s_add_i32 s76, s78, s6
	s_mov_b32 m0, s76
	ds_read_b128 v[206:209], v235
	ds_read_b128 v[226:229], v235 offset:2048
	ds_read_b128 v[222:225], v235 offset:1024
	ds_read_b128 v[230:233], v235 offset:3072
	global_load_lds_dwordx4 v170, s[92:93]
	s_add_i32 m0, s76, 0x2000
	s_nop 0
	global_load_lds_dwordx4 v174, s[92:93]
	s_waitcnt lgkmcnt(2)
	s_barrier
	v_mfma_f32_16x16x32_bf16 v[120:123], v[206:209], v[148:151], v[120:123]
	v_mfma_f32_16x16x32_bf16 v[116:119], v[226:229], v[148:151], v[116:119]
	v_mfma_f32_16x16x32_bf16 v[104:107], v[206:209], v[156:159], v[104:107]
	v_mfma_f32_16x16x32_bf16 v[100:103], v[226:229], v[156:159], v[100:103]
	v_mfma_f32_16x16x32_bf16 v[88:91], v[206:209], v[164:167], v[88:91]
	v_mfma_f32_16x16x32_bf16 v[84:87], v[226:229], v[164:167], v[84:87]
	v_mfma_f32_16x16x32_bf16 v[72:75], v[206:209], v[190:193], v[72:75]
	v_mfma_f32_16x16x32_bf16 v[68:71], v[226:229], v[190:193], v[68:71]
	s_waitcnt lgkmcnt(0)
	v_mfma_f32_16x16x32_bf16 v[120:123], v[222:225], v[152:155], v[120:123]
	v_mfma_f32_16x16x32_bf16 v[116:119], v[230:233], v[152:155], v[116:119]
	v_mfma_f32_16x16x32_bf16 v[104:107], v[222:225], v[160:163], v[104:107]
	v_mfma_f32_16x16x32_bf16 v[100:103], v[230:233], v[160:163], v[100:103]
	v_mfma_f32_16x16x32_bf16 v[88:91], v[222:225], v[186:189], v[88:91]
	v_mfma_f32_16x16x32_bf16 v[84:87], v[230:233], v[186:189], v[84:87]
	v_mfma_f32_16x16x32_bf16 v[72:75], v[222:225], v[202:205], v[72:75]
	v_mfma_f32_16x16x32_bf16 v[68:71], v[230:233], v[202:205], v[68:71]
	s_mov_b32 m0, s11
	s_barrier
	ds_read_b128 v[148:151], v200 offset:16384
	ds_read_b128 v[156:159], v200 offset:18432
	ds_read_b128 v[164:167], v200 offset:20480
	ds_read_b128 v[190:193], v200 offset:22528
	ds_read_b128 v[152:155], v200 offset:17408
	ds_read_b128 v[160:163], v200 offset:19456
	ds_read_b128 v[186:189], v200 offset:21504
	ds_read_b128 v[202:205], v200 offset:23552
	global_load_lds_dwordx4 v168, s[74:75]
	s_mov_b32 m0, s70
	s_nop 0
	global_load_lds_dwordx4 v172, s[74:75]
	s_waitcnt lgkmcnt(4)
	s_barrier
	v_mfma_f32_16x16x32_bf16 v[64:67], v[132:135], v[148:151], v[64:67]
	v_mfma_f32_16x16x32_bf16 v[60:63], v[140:143], v[148:151], v[60:63]
	v_mfma_f32_16x16x32_bf16 v[48:51], v[132:135], v[156:159], v[48:51]
	v_mfma_f32_16x16x32_bf16 v[44:47], v[140:143], v[156:159], v[44:47]
	v_mfma_f32_16x16x32_bf16 v[32:35], v[132:135], v[164:167], v[32:35]
	v_mfma_f32_16x16x32_bf16 v[28:31], v[140:143], v[164:167], v[28:31]
	v_mfma_f32_16x16x32_bf16 v[16:19], v[132:135], v[190:193], v[16:19]
	v_mfma_f32_16x16x32_bf16 v[12:15], v[140:143], v[190:193], v[12:15]
	s_waitcnt lgkmcnt(0)
	v_mfma_f32_16x16x32_bf16 v[64:67], v[136:139], v[152:155], v[64:67]
	v_mfma_f32_16x16x32_bf16 v[60:63], v[144:147], v[152:155], v[60:63]
	v_mfma_f32_16x16x32_bf16 v[48:51], v[136:139], v[160:163], v[48:51]
	v_mfma_f32_16x16x32_bf16 v[44:47], v[144:147], v[160:163], v[44:47]
	v_mfma_f32_16x16x32_bf16 v[32:35], v[136:139], v[186:189], v[32:35]
	v_mfma_f32_16x16x32_bf16 v[28:31], v[144:147], v[186:189], v[28:31]
	v_mfma_f32_16x16x32_bf16 v[16:19], v[136:139], v[202:205], v[16:19]
	v_mfma_f32_16x16x32_bf16 v[12:15], v[144:147], v[202:205], v[12:15]
	s_barrier
	s_add_u32 s76, s92, s13
	s_addc_u32 s77, s93, 0
	s_add_i32 s47, s47, s6
	s_mov_b32 m0, s47
	s_nop 0
	global_load_lds_dwordx4 v170, s[76:77]
	s_add_i32 m0, s47, 0x2000
	s_nop 0
	global_load_lds_dwordx4 v174, s[76:77]
	s_waitcnt vmcnt(6)
	s_barrier
; #define PG8_STAGE(bufoff, gbase, voff) do { _Pragma("unroll") for (int _i = 0; _i < 2; ++_i) \
;         __builtin_amdgcn_global_load_lds((const unsigned*)((const char*)(gbase) + (voff)[_i]), (LAS unsigned*)(lds + (bufoff) + ldsw + _i * 8192), 16, 0, 0); } while (0)
; #define PG8_LDA(dst, b, h) do { _Pragma("unroll") for (int m = 0; m < 4; ++m) _Pragma("unroll") for (int k = 0; k < 2; ++k) dst[m][k] = *(const LAS bf16x8*)(lds + PG8_SA(b, h) + aoff + m * 2048 + k * 1024); } while (0)
; #define PG8_LDB(dst, b, h) do { _Pragma("unroll") for (int n = 0; n < 2; ++n) _Pragma("unroll") for (int k = 0; k < 2; ++k) dst[n][k] = *(const LAS bf16x8*)(lds + PG8_SB(b, h) + boff + n * 2048 + k * 1024); } while (0)
; #define PG8_MMA(ai, bj, At, Bt) do { __builtin_amdgcn_s_setprio(1); _Pragma("unroll") for (int m = 0; m < 4; ++m) _Pragma("unroll") for (int n = 0; n < 2; ++n) _Pragma("unroll") for (int k = 0; k < 2; ++k) \
;         acc[ai][bj][m][n] = __builtin_amdgcn_mfma_f32_16x16x32_bf16(Bt[n][k], At[m][k], acc[ai][bj][m][n], 0, 0, 0); __builtin_amdgcn_s_setprio(0); } while (0)
; #define PG8_WAIT_V(n) asm volatile("s_waitcnt vmcnt(" #n ")" ::: "memory")
; #define PG8_WAIT_L(n) asm volatile("s_waitcnt lgkmcnt(" #n ")" ::: "memory")
; #define PG8_BAR __builtin_amdgcn_s_barrier()
; #define PG8_SCHED __builtin_amdgcn_sched_barrier(0)
; template <class Epi>
; __device__ __forceinline__ void gemm_phase(LAS unsigned char* lds, const Gemm g, const StaticOrder& S, const Epi& E) {
;     ...
;             PG8_WAIT_V(6); PG8_BAR; PG8_MMA(1, 1, At, B1); PG8_BAR;
;             PG8_LDB(B0, 1, 0); PG8_SCHED; PG8_LDA(At, 1, 0); PG8_STAGE(PG8_SA(0, 1), a2 + hstep, voffA);
;             PG8_WAIT_L(8); PG8_BAR; PG8_WAIT_L(0); PG8_MMA(0, 0, At, B0); PG8_BAR; PG8_SCHED;
;             PG8_LDB(B1, 1, 1); PG8_STAGE(PG8_SB(1, 0), b3, voffB);
;             PG8_BAR; PG8_WAIT_L(0); PG8_MMA(0, 1, At, B1); PG8_BAR;
	v_mfma_f32_16x16x32_bf16 v[56:59], v[206:209], v[148:151], v[56:59]
	v_mfma_f32_16x16x32_bf16 v[52:55], v[226:229], v[148:151], v[52:55]
	v_mfma_f32_16x16x32_bf16 v[40:43], v[206:209], v[156:159], v[40:43]
	v_mfma_f32_16x16x32_bf16 v[36:39], v[226:229], v[156:159], v[36:39]
	v_mfma_f32_16x16x32_bf16 v[24:27], v[206:209], v[164:167], v[24:27]
	v_mfma_f32_16x16x32_bf16 v[20:23], v[226:229], v[164:167], v[20:23]
	v_mfma_f32_16x16x32_bf16 v[8:11], v[206:209], v[190:193], v[8:11]
	v_mfma_f32_16x16x32_bf16 v[4:7], v[226:229], v[190:193], v[4:7]
	v_mfma_f32_16x16x32_bf16 v[56:59], v[222:225], v[152:155], v[56:59]
	v_mfma_f32_16x16x32_bf16 v[52:55], v[230:233], v[152:155], v[52:55]
	v_mfma_f32_16x16x32_bf16 v[40:43], v[222:225], v[160:163], v[40:43]
	v_mfma_f32_16x16x32_bf16 v[36:39], v[230:233], v[160:163], v[36:39]
	v_mfma_f32_16x16x32_bf16 v[24:27], v[222:225], v[186:189], v[24:27]
	v_mfma_f32_16x16x32_bf16 v[20:23], v[230:233], v[186:189], v[20:23]
	v_mfma_f32_16x16x32_bf16 v[8:11], v[222:225], v[202:205], v[8:11]
	v_mfma_f32_16x16x32_bf16 v[4:7], v[230:233], v[202:205], v[4:7]
	s_add_i32 s47, 0, 0x18000
	s_barrier
	ds_read_b128 v[132:135], v236
	ds_read_b128 v[140:143], v236 offset:2048
	ds_read_b128 v[148:151], v200 offset:32768
	ds_read_b128 v[156:159], v200 offset:34816
	s_add_u32 s76, s74, s13
	s_addc_u32 s77, s75, 0
	s_mov_b32 m0, s71
	ds_read_b128 v[164:167], v200 offset:36864
	ds_read_b128 v[190:193], v200 offset:38912
	ds_read_b128 v[136:139], v236 offset:1024
	ds_read_b128 v[144:147], v236 offset:3072
	ds_read_b128 v[152:155], v200 offset:33792
	ds_read_b128 v[160:163], v200 offset:35840
	ds_read_b128 v[186:189], v200 offset:37888
	ds_read_b128 v[202:205], v200 offset:39936
	global_load_lds_dwordx4 v168, s[76:77]
	s_mov_b32 m0, s19
	s_nop 0
	global_load_lds_dwordx4 v172, s[76:77]
	s_waitcnt lgkmcnt(6)
	s_barrier
	v_mfma_f32_16x16x32_bf16 v[128:131], v[132:135], v[148:151], v[128:131]
	v_mfma_f32_16x16x32_bf16 v[124:127], v[140:143], v[148:151], v[124:127]
	v_mfma_f32_16x16x32_bf16 v[112:115], v[132:135], v[156:159], v[112:115]
	v_mfma_f32_16x16x32_bf16 v[108:111], v[140:143], v[156:159], v[108:111]
	v_mfma_f32_16x16x32_bf16 v[96:99], v[132:135], v[164:167], v[96:99]
	v_mfma_f32_16x16x32_bf16 v[92:95], v[140:143], v[164:167], v[92:95]
	v_mfma_f32_16x16x32_bf16 v[80:83], v[132:135], v[190:193], v[80:83]
	v_mfma_f32_16x16x32_bf16 v[76:79], v[140:143], v[190:193], v[76:79]
	s_waitcnt lgkmcnt(0)
	v_mfma_f32_16x16x32_bf16 v[128:131], v[136:139], v[152:155], v[128:131]
	v_mfma_f32_16x16x32_bf16 v[124:127], v[144:147], v[152:155], v[124:127]
	v_mfma_f32_16x16x32_bf16 v[112:115], v[136:139], v[160:163], v[112:115]
	v_mfma_f32_16x16x32_bf16 v[108:111], v[144:147], v[160:163], v[108:111]
	v_mfma_f32_16x16x32_bf16 v[96:99], v[136:139], v[186:189], v[96:99]
	v_mfma_f32_16x16x32_bf16 v[92:95], v[144:147], v[186:189], v[92:95]
	v_mfma_f32_16x16x32_bf16 v[80:83], v[136:139], v[202:205], v[80:83]
	v_mfma_f32_16x16x32_bf16 v[76:79], v[144:147], v[202:205], v[76:79]
	s_barrier
	s_add_i32 s47, s47, s6
	s_add_u32 s76, s92, 0x80
	s_addc_u32 s77, s93, 0
	s_mov_b32 m0, s47
	ds_read_b128 v[206:209], v237
	ds_read_b128 v[226:229], v237 offset:2048
	ds_read_b128 v[222:225], v237 offset:1024
	ds_read_b128 v[230:233], v237 offset:3072
	global_load_lds_dwordx4 v170, s[76:77]
	s_add_i32 m0, s47, 0x2000
	s_nop 0
	global_load_lds_dwordx4 v174, s[76:77]
	s_waitcnt lgkmcnt(2)
	s_barrier
; #define PG8_STAGE(bufoff, gbase, voff) do { _Pragma("unroll") for (int _i = 0; _i < 2; ++_i) \
;         __builtin_amdgcn_global_load_lds((const unsigned*)((const char*)(gbase) + (voff)[_i]), (LAS unsigned*)(lds + (bufoff) + ldsw + _i * 8192), 16, 0, 0); } while (0)
; #define PG8_LDA(dst, b, h) do { _Pragma("unroll") for (int m = 0; m < 4; ++m) _Pragma("unroll") for (int k = 0; k < 2; ++k) dst[m][k] = *(const LAS bf16x8*)(lds + PG8_SA(b, h) + aoff + m * 2048 + k * 1024); } while (0)
; #define PG8_MMA(ai, bj, At, Bt) do { __builtin_amdgcn_s_setprio(1); _Pragma("unroll") for (int m = 0; m < 4; ++m) _Pragma("unroll") for (int n = 0; n < 2; ++n) _Pragma("unroll") for (int k = 0; k < 2; ++k) \
;         acc[ai][bj][m][n] = __builtin_amdgcn_mfma_f32_16x16x32_bf16(Bt[n][k], At[m][k], acc[ai][bj][m][n], 0, 0, 0); __builtin_amdgcn_s_setprio(0); } while (0)
; #define PG8_WAIT_V(n) asm volatile("s_waitcnt vmcnt(" #n ")" ::: "memory")
; #define PG8_WAIT_L(n) asm volatile("s_waitcnt lgkmcnt(" #n ")" ::: "memory")
; #define PG8_BAR __builtin_amdgcn_s_barrier()
; #define PG8_SCHED __builtin_amdgcn_sched_barrier(0)
; template <class Epi>
; __device__ __forceinline__ void gemm_phase(LAS unsigned char* lds, const Gemm g, const StaticOrder& S, const Epi& E) {
;     ...
;             PG8_BAR; PG8_WAIT_L(0); PG8_MMA(0, 1, At, B1); PG8_BAR;
;             PG8_LDA(At, 1, 1); PG8_STAGE(PG8_SA(1, 0), a3, voffA);
;             PG8_BAR; PG8_WAIT_L(0); PG8_MMA(1, 0, At, B0); PG8_BAR; PG8_SCHED;
;             PG8_STAGE(PG8_SB(1, 1), b3 + hstep, voffB);
;             PG8_WAIT_V(6); PG8_BAR; PG8_MMA(1, 1, At, B1); PG8_BAR;
	v_mfma_f32_16x16x32_bf16 v[120:123], v[206:209], v[148:151], v[120:123]
	v_mfma_f32_16x16x32_bf16 v[116:119], v[226:229], v[148:151], v[116:119]
	v_mfma_f32_16x16x32_bf16 v[104:107], v[206:209], v[156:159], v[104:107]
	v_mfma_f32_16x16x32_bf16 v[100:103], v[226:229], v[156:159], v[100:103]
	v_mfma_f32_16x16x32_bf16 v[88:91], v[206:209], v[164:167], v[88:91]
	v_mfma_f32_16x16x32_bf16 v[84:87], v[226:229], v[164:167], v[84:87]
	v_mfma_f32_16x16x32_bf16 v[72:75], v[206:209], v[190:193], v[72:75]
	v_mfma_f32_16x16x32_bf16 v[68:71], v[226:229], v[190:193], v[68:71]
	s_waitcnt lgkmcnt(0)
	v_mfma_f32_16x16x32_bf16 v[120:123], v[222:225], v[152:155], v[120:123]
	v_mfma_f32_16x16x32_bf16 v[116:119], v[230:233], v[152:155], v[116:119]
	v_mfma_f32_16x16x32_bf16 v[104:107], v[222:225], v[160:163], v[104:107]
	v_mfma_f32_16x16x32_bf16 v[100:103], v[230:233], v[160:163], v[100:103]
	v_mfma_f32_16x16x32_bf16 v[88:91], v[222:225], v[186:189], v[88:91]
	v_mfma_f32_16x16x32_bf16 v[84:87], v[230:233], v[186:189], v[84:87]
	v_mfma_f32_16x16x32_bf16 v[72:75], v[222:225], v[202:205], v[72:75]
	v_mfma_f32_16x16x32_bf16 v[68:71], v[230:233], v[202:205], v[68:71]
	s_mov_b32 m0, s33
	s_add_u32 s76, s74, 0x80
	s_addc_u32 s77, s75, 0
	s_barrier
	ds_read_b128 v[148:151], v200 offset:49152
	ds_read_b128 v[156:159], v200 offset:51200
	ds_read_b128 v[164:167], v200 offset:53248
	ds_read_b128 v[190:193], v200 offset:55296
	ds_read_b128 v[152:155], v200 offset:50176
	ds_read_b128 v[160:163], v200 offset:52224
	ds_read_b128 v[186:189], v200 offset:54272
	ds_read_b128 v[202:205], v200 offset:56320
	global_load_lds_dwordx4 v168, s[76:77]
	s_mov_b32 m0, s66
	s_nop 0
	global_load_lds_dwordx4 v172, s[76:77]
	s_waitcnt lgkmcnt(4)
	s_barrier
	v_mfma_f32_16x16x32_bf16 v[64:67], v[132:135], v[148:151], v[64:67]
	v_mfma_f32_16x16x32_bf16 v[60:63], v[140:143], v[148:151], v[60:63]
	v_mfma_f32_16x16x32_bf16 v[48:51], v[132:135], v[156:159], v[48:51]
	v_mfma_f32_16x16x32_bf16 v[44:47], v[140:143], v[156:159], v[44:47]
	v_mfma_f32_16x16x32_bf16 v[32:35], v[132:135], v[164:167], v[32:35]
	v_mfma_f32_16x16x32_bf16 v[28:31], v[140:143], v[164:167], v[28:31]
	v_mfma_f32_16x16x32_bf16 v[16:19], v[132:135], v[190:193], v[16:19]
	v_mfma_f32_16x16x32_bf16 v[12:15], v[140:143], v[190:193], v[12:15]
	s_waitcnt lgkmcnt(0)
	v_mfma_f32_16x16x32_bf16 v[64:67], v[136:139], v[152:155], v[64:67]
	v_mfma_f32_16x16x32_bf16 v[60:63], v[144:147], v[152:155], v[60:63]
	v_mfma_f32_16x16x32_bf16 v[48:51], v[136:139], v[160:163], v[48:51]
	v_mfma_f32_16x16x32_bf16 v[44:47], v[144:147], v[160:163], v[44:47]
	v_mfma_f32_16x16x32_bf16 v[32:35], v[136:139], v[186:189], v[32:35]
	v_mfma_f32_16x16x32_bf16 v[28:31], v[144:147], v[186:189], v[28:31]
	v_mfma_f32_16x16x32_bf16 v[16:19], v[136:139], v[202:205], v[16:19]
	v_mfma_f32_16x16x32_bf16 v[12:15], v[144:147], v[202:205], v[12:15]
	s_barrier
	s_add_i32 s47, s6, 0x1c000
	s_add_u32 s76, s92, s13
	s_addc_u32 s77, s93, 0
	s_add_u32 s76, s76, 0x80
	s_addc_u32 s77, s77, 0
	s_mov_b32 m0, s47
	s_nop 0
	global_load_lds_dwordx4 v170, s[76:77]
	s_add_i32 m0, s47, 0x2000
	s_nop 0
	global_load_lds_dwordx4 v174, s[76:77]
	s_waitcnt vmcnt(6)
	s_barrier
	v_mfma_f32_16x16x32_bf16 v[56:59], v[206:209], v[148:151], v[56:59]
	v_mfma_f32_16x16x32_bf16 v[52:55], v[226:229], v[148:151], v[52:55]
	v_mfma_f32_16x16x32_bf16 v[40:43], v[206:209], v[156:159], v[40:43]
	v_mfma_f32_16x16x32_bf16 v[36:39], v[226:229], v[156:159], v[36:39]
	v_mfma_f32_16x16x32_bf16 v[24:27], v[206:209], v[164:167], v[24:27]
	v_mfma_f32_16x16x32_bf16 v[20:23], v[226:229], v[164:167], v[20:23]
	v_mfma_f32_16x16x32_bf16 v[8:11], v[206:209], v[190:193], v[8:11]
	v_mfma_f32_16x16x32_bf16 v[4:7], v[226:229], v[190:193], v[4:7]
	v_mfma_f32_16x16x32_bf16 v[56:59], v[222:225], v[152:155], v[56:59]
	v_mfma_f32_16x16x32_bf16 v[52:55], v[230:233], v[152:155], v[52:55]
	v_mfma_f32_16x16x32_bf16 v[40:43], v[222:225], v[160:163], v[40:43]
	v_mfma_f32_16x16x32_bf16 v[36:39], v[230:233], v[160:163], v[36:39]
	v_mfma_f32_16x16x32_bf16 v[24:27], v[222:225], v[186:189], v[24:27]
	v_mfma_f32_16x16x32_bf16 v[20:23], v[230:233], v[186:189], v[20:23]
	v_mfma_f32_16x16x32_bf16 v[8:11], v[222:225], v[202:205], v[8:11]
	v_mfma_f32_16x16x32_bf16 v[4:7], v[230:233], v[202:205], v[4:7]
	s_add_u32 s3, s3, 0x100
	s_addc_u32 vcc_lo, vcc_lo, 0
	s_add_u32 vcc_hi, vcc_hi, 0x100
	s_addc_u32 s46, s46, 0
	s_cmp_lt_i32 s2, s57
	s_barrier
	s_cbranch_scc1 .LBB0_206
	s_movk_i32 s92, 0x90
	s_mov_b32 s93, 0x3f317217
